# NSA compressed branch pass 1: fast path for fully valid 64-key sub-tiles
# speedup vs baseline: 1.0003x; 1.0003x over previous
.LBB0_239:
	s_lshl_b32 s0, s2, 10
	s_or_b32 s0, s0, s86
	s_or_b32 s1, s0, 28
	v_cmp_le_i32_e32 vcc, s1, v176
	s_and_saveexec_b64 s[70:71], vcc
	s_cbranch_execz .LBB0_238
	s_mul_i32 s1, s2, 0x2400
	v_readfirstlane_b32 s46, v176
	s_add_i32 s47, s0, 0x40f
	s_cmp_le_i32 s47, s46
	s_cbranch_scc0 .Lnsa_cmp1_slow
	v_add_u32_e32 v62, s1, v61
	ds_read_b128 v[34:37], v62
	ds_read_b128 v[38:41], v62 offset:4608
	ds_read_b128 v[42:45], v62 offset:32
	ds_read_b128 v[64:67], v62 offset:4640
	ds_read_b128 v[68:71], v62 offset:64
	ds_read_b128 v[72:75], v62 offset:4672
	s_waitcnt lgkmcnt(4)
	v_mfma_f32_32x32x16_bf16 v[2:17], v[34:37], v[80:83], 0
	v_mfma_f32_32x32x16_bf16 v[18:33], v[38:41], v[80:83], 0
	s_waitcnt lgkmcnt(2)
	v_mfma_f32_32x32x16_bf16 v[2:17], v[42:45], v[84:87], v[2:17]
	v_mfma_f32_32x32x16_bf16 v[18:33], v[64:67], v[84:87], v[18:33]
	ds_read_b128 v[34:37], v62 offset:96
	ds_read_b128 v[38:41], v62 offset:4704
	s_waitcnt lgkmcnt(2)
	v_mfma_f32_32x32x16_bf16 v[2:17], v[68:71], v[88:91], v[2:17]
	v_mfma_f32_32x32x16_bf16 v[18:33], v[72:75], v[88:91], v[18:33]
	s_waitcnt lgkmcnt(0)
	v_mfma_f32_32x32x16_bf16 v[2:17], v[34:37], v[92:95], v[2:17]
	v_mfma_f32_32x32x16_bf16 v[18:33], v[38:41], v[92:95], v[18:33]
	v_mul_f32_e64 v42, -1.0, s80
	v_mov_b32_e32 v62, 0x3e38aa3b
	v_mov_b64_e32 v[76:77], 0
	s_nop 7
	s_nop 0
	v_pk_fma_f32 v[2:3], v[2:3], v[62:63], v[42:43] op_sel_hi:[1,0,0]
	v_pk_fma_f32 v[4:5], v[4:5], v[62:63], v[42:43] op_sel_hi:[1,0,0]
	v_pk_fma_f32 v[6:7], v[6:7], v[62:63], v[42:43] op_sel_hi:[1,0,0]
	v_pk_fma_f32 v[8:9], v[8:9], v[62:63], v[42:43] op_sel_hi:[1,0,0]
	v_pk_fma_f32 v[10:11], v[10:11], v[62:63], v[42:43] op_sel_hi:[1,0,0]
	v_pk_fma_f32 v[12:13], v[12:13], v[62:63], v[42:43] op_sel_hi:[1,0,0]
	v_pk_fma_f32 v[14:15], v[14:15], v[62:63], v[42:43] op_sel_hi:[1,0,0]
	v_pk_fma_f32 v[16:17], v[16:17], v[62:63], v[42:43] op_sel_hi:[1,0,0]
	v_exp_f32_e32 v2, v2
	v_exp_f32_e32 v3, v3
	v_exp_f32_e32 v4, v4
	v_exp_f32_e32 v5, v5
	v_exp_f32_e32 v6, v6
	v_exp_f32_e32 v7, v7
	v_exp_f32_e32 v8, v8
	v_exp_f32_e32 v9, v9
	v_exp_f32_e32 v10, v10
	v_exp_f32_e32 v11, v11
	v_exp_f32_e32 v12, v12
	v_exp_f32_e32 v13, v13
	v_exp_f32_e32 v14, v14
	v_exp_f32_e32 v15, v15
	v_exp_f32_e32 v16, v16
	v_exp_f32_e32 v17, v17
	v_pk_fma_f32 v[18:19], v[18:19], v[62:63], v[42:43] op_sel_hi:[1,0,0]
	v_pk_fma_f32 v[20:21], v[20:21], v[62:63], v[42:43] op_sel_hi:[1,0,0]
	v_pk_fma_f32 v[22:23], v[22:23], v[62:63], v[42:43] op_sel_hi:[1,0,0]
	v_pk_fma_f32 v[24:25], v[24:25], v[62:63], v[42:43] op_sel_hi:[1,0,0]
	v_pk_fma_f32 v[26:27], v[26:27], v[62:63], v[42:43] op_sel_hi:[1,0,0]
	v_pk_fma_f32 v[28:29], v[28:29], v[62:63], v[42:43] op_sel_hi:[1,0,0]
	v_pk_fma_f32 v[30:31], v[30:31], v[62:63], v[42:43] op_sel_hi:[1,0,0]
	v_pk_fma_f32 v[32:33], v[32:33], v[62:63], v[42:43] op_sel_hi:[1,0,0]
	v_exp_f32_e32 v18, v18
	v_exp_f32_e32 v19, v19
	v_exp_f32_e32 v20, v20
	v_exp_f32_e32 v21, v21
	v_exp_f32_e32 v22, v22
	v_exp_f32_e32 v23, v23
	v_exp_f32_e32 v24, v24
	v_exp_f32_e32 v25, v25
	v_exp_f32_e32 v26, v26
	v_exp_f32_e32 v27, v27
	v_exp_f32_e32 v28, v28
	v_exp_f32_e32 v29, v29
	v_exp_f32_e32 v30, v30
	v_exp_f32_e32 v31, v31
	v_exp_f32_e32 v32, v32
	v_exp_f32_e32 v33, v33
	v_pk_add_f32 v[76:77], v[2:3], v[76:77]
	v_pk_add_f32 v[76:77], v[4:5], v[76:77]
	v_pk_add_f32 v[76:77], v[6:7], v[76:77]
	v_pk_add_f32 v[76:77], v[8:9], v[76:77]
	v_pk_add_f32 v[76:77], v[10:11], v[76:77]
	v_pk_add_f32 v[76:77], v[12:13], v[76:77]
	v_pk_add_f32 v[76:77], v[14:15], v[76:77]
	v_pk_add_f32 v[76:77], v[16:17], v[76:77]
	v_pk_add_f32 v[76:77], v[18:19], v[76:77]
	v_pk_add_f32 v[76:77], v[20:21], v[76:77]
	v_pk_add_f32 v[76:77], v[22:23], v[76:77]
	v_pk_add_f32 v[76:77], v[24:25], v[76:77]
	v_pk_add_f32 v[76:77], v[26:27], v[76:77]
	v_pk_add_f32 v[76:77], v[28:29], v[76:77]
	v_pk_add_f32 v[76:77], v[30:31], v[76:77]
	v_pk_add_f32 v[76:77], v[32:33], v[76:77]
	v_add_f32_e32 v1, v1, v76
	v_add_f32_e32 v1, v1, v77
	s_branch .LBB0_238
.Lnsa_cmp1_slow:
	v_add_u32_e32 v26, s1, v61
	ds_read_b128 v[18:21], v26 offset:4608
	ds_read_b128 v[2:5], v26
	ds_read_b128 v[22:25], v26 offset:32
	ds_read_b128 v[42:45], v26 offset:4640
	s_waitcnt lgkmcnt(0)
	v_mfma_f32_32x32x16_bf16 v[2:17], v[2:5], v[80:83], 0
	v_mfma_f32_32x32x16_bf16 v[2:17], v[22:25], v[84:87], v[2:17]
	ds_read_b128 v[22:25], v26 offset:64
	ds_read_b128 v[38:41], v26 offset:4672
	s_waitcnt lgkmcnt(0)
	v_mfma_f32_32x32x16_bf16 v[2:17], v[22:25], v[88:91], v[2:17]
	ds_read_b128 v[22:25], v26 offset:96
	ds_read_b128 v[34:37], v26 offset:4704
	s_waitcnt lgkmcnt(0)
	v_mfma_f32_32x32x16_bf16 v[2:17], v[22:25], v[92:95], v[2:17]
	v_or_b32_e32 v22, s0, v153
	v_or_b32_e32 v69, 0x12f, v22
	v_or_b32_e32 v75, 0x19f, v22
	v_or_b32_e32 v77, 0x1af, v22
	v_or_b32_e32 v23, 47, v22
	v_or_b32_e32 v67, 0x11f, v22
	v_cmp_gt_i32_e64 s[46:47], v69, v122
	v_cmp_gt_i32_e64 s[52:53], v75, v122
	v_cmp_gt_i32_e64 s[54:55], v77, v122
	v_cmp_gt_i32_e64 s[2:3], v23, v122
	v_or_b32_e32 v33, 0xbf, v22
	v_add_u32_e32 v65, 0xcf, v22
	v_cmp_gt_i32_e64 s[44:45], v67, v122
	v_cndmask_b32_e64 v69, v233, 0, s[46:47]
	v_cndmask_b32_e64 v75, v228, 0, s[52:53]
	v_cndmask_b32_e64 v77, v227, 0, s[54:55]
	v_cndmask_b32_e64 v23, 2, 0, s[2:3]
	v_or_b32_e32 v25, 63, v22
	v_add_u32_e32 v27, 0x4f, v22
	v_cmp_gt_i32_e64 s[38:39], v33, v122
	v_cmp_gt_i32_e64 s[42:43], v65, v122
	v_cndmask_b32_e64 v67, v232, 0, s[44:45]
	v_or3_b32 v69, v69, v75, v77
	v_cmp_gt_i32_e64 s[6:7], v25, v122
	v_cmp_gt_i32_e64 s[8:9], v27, v122
	v_cndmask_b32_e64 v33, 64, 0, s[38:39]
	v_cndmask_b32_e64 v65, v231, 0, s[42:43]
	v_or3_b32 v23, v67, v23, v69
	v_cndmask_b32_e64 v25, 4, 0, s[6:7]
	v_cndmask_b32_e64 v27, 8, 0, s[8:9]
	v_or3_b32 v23, v33, v65, v23
	v_or_b32_e32 v70, 0x32f, v22
	v_or_b32_e32 v76, 0x39f, v22
	v_or3_b32 v23, v25, v27, v23
	v_or_b32_e32 v25, 0x3af, v22
	v_or_b32_e32 v24, 0x22f, v22
	v_or_b32_e32 v68, 0x31f, v22
	v_cmp_gt_i32_e64 s[20:21], v70, v122
	v_cmp_gt_i32_e64 s[26:27], v76, v122
	v_cmp_gt_i32_e64 s[28:29], v25, v122
	v_cmp_gt_i32_e32 vcc, v24, v122
	v_or_b32_e32 v64, 0x2bf, v22
	v_add_u32_e32 v66, 0x2cf, v22
	v_cmp_gt_i32_e64 s[18:19], v68, v122
	v_cndmask_b32_e64 v70, v233, 0, s[20:21]
	v_cndmask_b32_e64 v76, v228, 0, s[26:27]
	v_cndmask_b32_e64 v25, v227, 0, s[28:29]
	v_cndmask_b32_e64 v24, 2, 0, vcc
	v_or_b32_e32 v26, 0x23f, v22
	v_add_u32_e32 v28, 0x24f, v22
	v_cmp_gt_i32_e64 s[14:15], v64, v122
	v_cmp_gt_i32_e64 s[16:17], v66, v122
	v_cndmask_b32_e64 v68, v232, 0, s[18:19]
	v_or3_b32 v25, v70, v76, v25
	v_cmp_gt_i32_e64 s[0:1], v26, v122
	v_cmp_gt_i32_e64 s[4:5], v28, v122
	v_cndmask_b32_e64 v64, 64, 0, s[14:15]
	v_cndmask_b32_e64 v66, v231, 0, s[16:17]
	v_or3_b32 v24, v68, v24, v25
	v_cndmask_b32_e64 v26, 4, 0, s[0:1]
	v_cndmask_b32_e64 v28, 8, 0, s[4:5]
	v_or3_b32 v24, v64, v66, v24
	v_or_b32_e32 v25, 0x1bf, v22
	v_or_b32_e32 v29, 0x9f, v22
	v_or_b32_e32 v30, 0x29f, v22
	v_or_b32_e32 v71, 0x13f, v22
	v_or_b32_e32 v72, 0x33f, v22
	v_or3_b32 v24, v26, v28, v24
	v_cmp_gt_i32_e64 s[56:57], v25, v122
	v_or_b32_e32 v26, 0x3bf, v22
	v_cmp_gt_i32_e64 s[30:31], v29, v122
	v_cmp_gt_i32_e64 s[10:11], v30, v122
	v_or_b32_e32 v31, 0xaf, v22
	v_or_b32_e32 v32, 0x2af, v22
	v_cmp_gt_i32_e64 s[48:49], v71, v122
	v_cmp_gt_i32_e64 s[22:23], v72, v122
	v_add_u32_e32 v73, 0x14f, v22
	v_add_u32_e32 v74, 0x34f, v22
	v_cndmask_b32_e64 v25, v225, 0, s[56:57]
	v_cmp_gt_i32_e64 s[56:57], v26, v122
	v_add_u32_e32 v27, 0x1cf, v22
	v_or_b32_e32 v62, 31, v22
	v_or_b32_e32 v63, 0x21f, v22
	v_cndmask_b32_e64 v29, 16, 0, s[30:31]
	v_cndmask_b32_e64 v30, 16, 0, s[10:11]
	v_cmp_gt_i32_e64 s[34:35], v31, v122
	v_cmp_gt_i32_e64 s[12:13], v32, v122
	v_cndmask_b32_e64 v71, v230, 0, s[48:49]
	v_cndmask_b32_e64 v72, v230, 0, s[22:23]
	v_cmp_gt_i32_e64 s[50:51], v73, v122
	v_cmp_gt_i32_e64 s[24:25], v74, v122
	v_cndmask_b32_e64 v26, v225, 0, s[56:57]
	v_cmp_gt_i32_e64 s[56:57], v27, v122
	v_add_u32_e32 v22, 0x3cf, v22
	v_cndmask_b32_e64 v31, 32, 0, s[34:35]
	v_cndmask_b32_e64 v32, 32, 0, s[12:13]
	v_cndmask_b32_e64 v73, v229, 0, s[50:51]
	v_cndmask_b32_e64 v74, v229, 0, s[24:25]
	v_or3_b32 v23, v29, v71, v23
	v_or3_b32 v24, v30, v72, v24
	v_cndmask_b32_e64 v27, v226, 0, s[56:57]
	v_cmp_gt_i32_e64 s[56:57], v22, v122
	v_or3_b32 v23, v31, v73, v23
	v_or3_b32 v24, v32, v74, v24
	v_cndmask_b32_e64 v22, v226, 0, s[56:57]
	v_or3_b32 v64, v25, v27, v23
	v_or3_b32 v65, v26, v22, v24
	v_mfma_f32_32x32x16_bf16 v[18:33], v[18:21], v[80:83], 0
	v_mov_b32_e32 v66, s80
	v_fma_f32 v3, v3, s33, -v66
	v_cndmask_b32_e64 v3, v3, v234, s[2:3]
	v_cmp_le_i32_e64 s[56:57], v62, v122
	v_fma_f32 v2, v2, s33, -v66
	s_nop 0
	v_cndmask_b32_e64 v2, v234, v2, s[56:57]
	v_mfma_f32_32x32x16_bf16 v[18:33], v[42:45], v[84:87], v[18:33]
	v_exp_f32_e32 v2, v2
	v_mfma_f32_32x32x16_bf16 v[18:33], v[38:41], v[88:91], v[18:33]
	v_mfma_f32_32x32x16_bf16 v[18:33], v[34:37], v[92:95], v[18:33]
	v_exp_f32_e32 v34, v3
	v_fma_f32 v3, v4, s33, -v66
	v_cndmask_b32_e64 v3, v3, v234, s[6:7]
	v_exp_f32_e32 v4, v3
	v_fma_f32 v3, v5, s33, -v66
	v_cndmask_b32_e64 v3, v3, v234, s[8:9]
	v_exp_f32_e32 v36, v3
	v_fma_f32 v3, v6, s33, -v66
	v_cndmask_b32_e64 v3, v3, v234, s[30:31]
	v_exp_f32_e32 v6, v3
	v_fma_f32 v3, v7, s33, -v66
	v_cndmask_b32_e64 v3, v3, v234, s[34:35]
	v_exp_f32_e32 v38, v3
	v_fma_f32 v3, v8, s33, -v66
	v_cndmask_b32_e64 v3, v3, v234, s[38:39]
	v_exp_f32_e32 v8, v3
	v_fma_f32 v3, v9, s33, -v66
	v_cndmask_b32_e64 v3, v3, v234, s[42:43]
	v_exp_f32_e32 v40, v3
	v_fma_f32 v3, v10, s33, -v66
	v_cndmask_b32_e64 v3, v3, v234, s[44:45]
	v_exp_f32_e32 v10, v3
	v_fma_f32 v3, v11, s33, -v66
	v_cndmask_b32_e64 v3, v3, v234, s[46:47]
	v_exp_f32_e32 v42, v3
	v_fma_f32 v3, v12, s33, -v66
	v_cndmask_b32_e64 v3, v3, v234, s[48:49]
	v_exp_f32_e32 v12, v3
	v_fma_f32 v3, v13, s33, -v66
	v_cndmask_b32_e64 v3, v3, v234, s[50:51]
	v_exp_f32_e32 v44, v3
	v_fma_f32 v3, v14, s33, -v66
	v_cndmask_b32_e64 v3, v3, v234, s[52:53]
	v_exp_f32_e32 v14, v3
	v_fma_f32 v3, v15, s33, -v66
	v_cndmask_b32_e64 v3, v3, v234, s[54:55]
	v_and_b32_e32 v5, 0x4000, v64
	v_exp_f32_e32 v62, v3
	v_fma_f32 v3, v16, s33, -v66
	v_cmp_ne_u32_e64 s[2:3], 0, v5
	v_and_b32_e32 v5, 0x8000, v64
	v_fma_f32 v7, v21, s33, -v66
	v_cndmask_b32_e64 v3, v234, v3, s[2:3]
	v_exp_f32_e32 v16, v3
	v_fma_f32 v3, v17, s33, -v66
	v_cmp_ne_u32_e64 s[2:3], 0, v5
	v_fma_f32 v5, v19, s33, -v66
	v_cndmask_b32_e32 v5, v5, v234, vcc
	v_cndmask_b32_e64 v3, v234, v3, s[2:3]
	v_exp_f32_e32 v64, v3
	v_fma_f32 v3, v18, s33, -v66
	v_cmp_le_i32_e64 s[2:3], v63, v122
	v_exp_f32_e32 v35, v5
	v_fma_f32 v5, v20, s33, -v66
	v_cndmask_b32_e64 v3, v234, v3, s[2:3]
	v_exp_f32_e32 v3, v3
	v_cndmask_b32_e64 v5, v5, v234, s[0:1]
	v_exp_f32_e32 v5, v5
	v_cndmask_b32_e64 v7, v7, v234, s[4:5]
	v_pk_add_f32 v[2:3], v[2:3], 0 op_sel_hi:[1,0]
	v_exp_f32_e32 v37, v7
	v_pk_add_f32 v[2:3], v[34:35], v[2:3]
	s_nop 0
	v_pk_add_f32 v[2:3], v[4:5], v[2:3]
	v_fma_f32 v4, v22, s33, -v66
	v_cndmask_b32_e64 v4, v4, v234, s[10:11]
	v_exp_f32_e32 v7, v4
	v_fma_f32 v4, v23, s33, -v66
	v_cndmask_b32_e64 v4, v4, v234, s[12:13]
	v_exp_f32_e32 v39, v4
	v_fma_f32 v4, v24, s33, -v66
	v_cndmask_b32_e64 v4, v4, v234, s[14:15]
	v_exp_f32_e32 v9, v4
	v_fma_f32 v4, v25, s33, -v66
	v_cndmask_b32_e64 v4, v4, v234, s[16:17]
	v_exp_f32_e32 v41, v4
	v_fma_f32 v4, v26, s33, -v66
	v_cndmask_b32_e64 v4, v4, v234, s[18:19]
	v_exp_f32_e32 v11, v4
	v_fma_f32 v4, v27, s33, -v66
	v_cndmask_b32_e64 v4, v4, v234, s[20:21]
	v_exp_f32_e32 v43, v4
	v_fma_f32 v4, v28, s33, -v66
	v_cndmask_b32_e64 v4, v4, v234, s[22:23]
	v_exp_f32_e32 v13, v4
	v_fma_f32 v4, v29, s33, -v66
	v_cndmask_b32_e64 v4, v4, v234, s[24:25]
	v_pk_add_f32 v[2:3], v[36:37], v[2:3]
	v_exp_f32_e32 v45, v4
	v_fma_f32 v4, v30, s33, -v66
	v_cndmask_b32_e64 v4, v4, v234, s[26:27]
	v_pk_add_f32 v[2:3], v[6:7], v[2:3]
	v_exp_f32_e32 v15, v4
	v_fma_f32 v4, v31, s33, -v66
	v_pk_add_f32 v[2:3], v[38:39], v[2:3]
	v_cndmask_b32_e64 v4, v4, v234, s[28:29]
	v_and_b32_e32 v5, 0x4000, v65
	v_pk_add_f32 v[2:3], v[8:9], v[2:3]
	v_exp_f32_e32 v63, v4
	v_fma_f32 v4, v32, s33, -v66
	v_cmp_ne_u32_e32 vcc, 0, v5
	v_pk_add_f32 v[2:3], v[40:41], v[2:3]
	v_and_b32_e32 v5, 0x8000, v65
	v_cndmask_b32_e32 v4, v234, v4, vcc
	v_pk_add_f32 v[2:3], v[10:11], v[2:3]
	v_exp_f32_e32 v17, v4
	v_fma_f32 v4, v33, s33, -v66
	v_cmp_ne_u32_e32 vcc, 0, v5
	v_pk_add_f32 v[2:3], v[42:43], v[2:3]
	s_nop 0
	v_cndmask_b32_e32 v4, v234, v4, vcc
	v_pk_add_f32 v[2:3], v[12:13], v[2:3]
	v_exp_f32_e32 v65, v4
	v_pk_add_f32 v[2:3], v[44:45], v[2:3]
	s_nop 0
	v_pk_add_f32 v[2:3], v[14:15], v[2:3]
	s_nop 0
	v_pk_add_f32 v[2:3], v[62:63], v[2:3]
	s_nop 0
	v_pk_add_f32 v[2:3], v[16:17], v[2:3]
	s_nop 0
	v_pk_add_f32 v[2:3], v[64:65], v[2:3]
	s_nop 0
	v_add_f32_e32 v1, v1, v2
	v_add_f32_e32 v1, v1, v3
	s_branch .LBB0_238
